# G2/G4 epilogue row sums also via v_permlane16/32_swap instead of ds_bpermute round trips
# baseline (speedup 1.0000x reference)
.LBB0_370:
	v_mul_f32_e32 v127, v127, v127
	v_mul_f32_e32 v123, v123, v123
	v_mul_f32_e32 v119, v119, v119
	v_mul_f32_e32 v115, v115, v115
	v_fmac_f32_e32 v127, v126, v126
	v_mul_f32_e32 v126, v129, v129
	v_fmac_f32_e32 v123, v122, v122
	v_mul_f32_e32 v122, v125, v125
	v_fmac_f32_e32 v119, v118, v118
	v_mul_f32_e32 v118, v121, v121
	v_fmac_f32_e32 v115, v114, v114
	v_mul_f32_e32 v114, v117, v117
	v_fmac_f32_e32 v126, v128, v128
	v_fmac_f32_e32 v122, v124, v124
	v_fmac_f32_e32 v118, v120, v120
	v_fmac_f32_e32 v114, v116, v116
	v_add_f32_e32 v126, v127, v126
	v_add_f32_e32 v122, v123, v122
	v_add_f32_e32 v118, v119, v118
	v_add_f32_e32 v114, v115, v114
	v_add_f32_e32 v122, v126, v122
	v_add_f32_e32 v114, v118, v114
	v_add_f32_e32 v114, v122, v114
	v_mov_b32_e32 v115, v114
	s_nop 1
	v_permlane16_swap_b32 v114, v115
	s_nop 1
	v_add_f32_e32 v114, v114, v115
	s_lshl_b32 s72, s27, 2
	s_ashr_i32 s73, s72, 31
	v_mov_b32_e32 v115, v114
	s_nop 1
	v_permlane32_swap_b32 v114, v115
	s_nop 1
	s_and_saveexec_b64 s[56:57], s[36:37]
	s_cbranch_execz .LBB0_372
	v_lshlrev_b64 v[116:117], 6, v[174:175]
	v_lshl_add_u64 v[116:117], s[48:49], 0, v[116:117]
	v_lshl_add_u64 v[116:117], s[72:73], 2, v[116:117]
	s_lshl_b32 s50, s77, 2
	v_lshl_add_u64 v[116:117], v[116:117], 0, s[50:51]
	s_waitcnt lgkmcnt(0)
	v_add_f32_e32 v114, v114, v115
	global_store_dword v[116:117], v114, off

.LBB0_378:
	v_mul_f32_e32 v111, v111, v111
	v_mul_f32_e32 v107, v107, v107
	v_mul_f32_e32 v103, v103, v103
	v_mul_f32_e32 v99, v99, v99
	v_fmac_f32_e32 v111, v110, v110
	v_mul_f32_e32 v110, v113, v113
	v_fmac_f32_e32 v107, v106, v106
	v_mul_f32_e32 v106, v109, v109
	v_fmac_f32_e32 v103, v102, v102
	v_mul_f32_e32 v102, v105, v105
	v_fmac_f32_e32 v99, v98, v98
	v_mul_f32_e32 v98, v101, v101
	v_fmac_f32_e32 v110, v112, v112
	v_fmac_f32_e32 v106, v108, v108
	v_fmac_f32_e32 v102, v104, v104
	v_fmac_f32_e32 v98, v100, v100
	v_add_f32_e32 v110, v111, v110
	v_add_f32_e32 v106, v107, v106
	v_add_f32_e32 v102, v103, v102
	v_add_f32_e32 v98, v99, v98
	v_add_f32_e32 v106, v110, v106
	v_add_f32_e32 v98, v102, v98
	v_add_f32_e32 v98, v106, v98
	v_mov_b32_e32 v99, v98
	s_nop 1
	v_permlane16_swap_b32 v98, v99
	s_nop 1
	v_add_f32_e32 v98, v98, v99
	v_mov_b32_e32 v99, v98
	s_nop 1
	v_permlane32_swap_b32 v98, v99
	s_nop 1
	s_and_saveexec_b64 s[56:57], s[36:37]
	s_cbranch_execz .LBB0_380
	v_lshlrev_b64 v[100:101], 6, v[184:185]
	v_lshl_add_u64 v[100:101], s[48:49], 0, v[100:101]
	v_lshl_add_u64 v[100:101], s[72:73], 2, v[100:101]
	s_lshl_b32 s50, s77, 2
	v_lshl_add_u64 v[100:101], v[100:101], 0, s[50:51]
	s_waitcnt lgkmcnt(0)
	v_add_f32_e32 v98, v98, v99
	global_store_dword v[100:101], v98, off

.LBB0_386:
	v_mul_f32_e32 v95, v95, v95
	v_mul_f32_e32 v91, v91, v91
	v_mul_f32_e32 v87, v87, v87
	v_mul_f32_e32 v83, v83, v83
	v_fmac_f32_e32 v95, v94, v94
	v_mul_f32_e32 v94, v97, v97
	v_fmac_f32_e32 v91, v90, v90
	v_mul_f32_e32 v90, v93, v93
	v_fmac_f32_e32 v87, v86, v86
	v_mul_f32_e32 v86, v89, v89
	v_fmac_f32_e32 v83, v82, v82
	v_mul_f32_e32 v82, v85, v85
	v_fmac_f32_e32 v94, v96, v96
	v_fmac_f32_e32 v90, v92, v92
	v_fmac_f32_e32 v86, v88, v88
	v_fmac_f32_e32 v82, v84, v84
	v_add_f32_e32 v94, v95, v94
	v_add_f32_e32 v90, v91, v90
	v_add_f32_e32 v86, v87, v86
	v_add_f32_e32 v82, v83, v82
	v_add_f32_e32 v90, v94, v90
	v_add_f32_e32 v82, v86, v82
	v_add_f32_e32 v82, v90, v82
	v_mov_b32_e32 v83, v82
	s_nop 1
	v_permlane16_swap_b32 v82, v83
	s_nop 1
	v_add_f32_e32 v82, v82, v83
	v_mov_b32_e32 v83, v82
	s_nop 1
	v_permlane32_swap_b32 v82, v83
	s_nop 1
	s_and_saveexec_b64 s[56:57], s[36:37]
	s_cbranch_execz .LBB0_388
	v_lshlrev_b64 v[84:85], 6, v[180:181]
	v_lshl_add_u64 v[84:85], s[48:49], 0, v[84:85]
	v_lshl_add_u64 v[84:85], s[72:73], 2, v[84:85]
	s_lshl_b32 s50, s77, 2
	v_lshl_add_u64 v[84:85], v[84:85], 0, s[50:51]
	s_waitcnt lgkmcnt(0)
	v_add_f32_e32 v82, v82, v83
	global_store_dword v[84:85], v82, off

.LBB0_394:
	v_mul_f32_e32 v79, v79, v79
	v_mul_f32_e32 v75, v75, v75
	v_mul_f32_e32 v71, v71, v71
	v_mul_f32_e32 v67, v67, v67
	v_fmac_f32_e32 v79, v78, v78
	v_mul_f32_e32 v78, v81, v81
	v_fmac_f32_e32 v75, v74, v74
	v_mul_f32_e32 v74, v77, v77
	v_fmac_f32_e32 v71, v70, v70
	v_mul_f32_e32 v70, v73, v73
	v_fmac_f32_e32 v67, v66, v66
	v_mul_f32_e32 v66, v69, v69
	v_fmac_f32_e32 v78, v80, v80
	v_fmac_f32_e32 v74, v76, v76
	v_fmac_f32_e32 v70, v72, v72
	v_fmac_f32_e32 v66, v68, v68
	v_add_f32_e32 v78, v79, v78
	v_add_f32_e32 v74, v75, v74
	v_add_f32_e32 v70, v71, v70
	v_add_f32_e32 v66, v67, v66
	v_add_f32_e32 v74, v78, v74
	v_add_f32_e32 v66, v70, v66
	v_add_f32_e32 v66, v74, v66
	v_mov_b32_e32 v67, v66
	s_nop 1
	v_permlane16_swap_b32 v66, v67
	s_nop 1
	v_add_f32_e32 v66, v66, v67
	v_mov_b32_e32 v67, v66
	s_nop 1
	v_permlane32_swap_b32 v66, v67
	s_nop 1
	s_and_saveexec_b64 s[56:57], s[36:37]
	s_cbranch_execz .LBB0_396
	v_lshlrev_b64 v[68:69], 6, v[176:177]
	v_lshl_add_u64 v[68:69], s[48:49], 0, v[68:69]
	v_lshl_add_u64 v[68:69], s[72:73], 2, v[68:69]
	s_lshl_b32 s50, s77, 2
	v_lshl_add_u64 v[68:69], v[68:69], 0, s[50:51]
	s_waitcnt lgkmcnt(0)
	v_add_f32_e32 v66, v66, v67
	global_store_dword v[68:69], v66, off

.LBB0_402:
	v_mul_f32_e32 v63, v63, v63
	v_mul_f32_e32 v59, v59, v59
	v_mul_f32_e32 v55, v55, v55
	v_mul_f32_e32 v51, v51, v51
	v_fmac_f32_e32 v63, v62, v62
	v_mul_f32_e32 v62, v65, v65
	v_fmac_f32_e32 v59, v58, v58
	v_mul_f32_e32 v58, v61, v61
	v_fmac_f32_e32 v55, v54, v54
	v_mul_f32_e32 v54, v57, v57
	v_fmac_f32_e32 v51, v50, v50
	v_mul_f32_e32 v50, v53, v53
	v_fmac_f32_e32 v62, v64, v64
	v_fmac_f32_e32 v58, v60, v60
	v_fmac_f32_e32 v54, v56, v56
	v_fmac_f32_e32 v50, v52, v52
	v_add_f32_e32 v62, v63, v62
	v_add_f32_e32 v58, v59, v58
	v_add_f32_e32 v54, v55, v54
	v_add_f32_e32 v50, v51, v50
	v_add_f32_e32 v58, v62, v58
	v_add_f32_e32 v50, v54, v50
	v_add_f32_e32 v50, v58, v50
	v_mov_b32_e32 v51, v50
	s_nop 1
	v_permlane16_swap_b32 v50, v51
	s_nop 1
	v_add_f32_e32 v50, v50, v51
	v_mov_b32_e32 v51, v50
	s_nop 1
	v_permlane32_swap_b32 v50, v51
	s_nop 1
	s_and_saveexec_b64 s[56:57], s[36:37]
	s_cbranch_execz .LBB0_404
	v_lshlrev_b64 v[52:53], 6, v[106:107]
	v_lshl_add_u64 v[52:53], s[48:49], 0, v[52:53]
	v_lshl_add_u64 v[52:53], s[72:73], 2, v[52:53]
	s_lshl_b32 s50, s77, 2
	v_lshl_add_u64 v[52:53], v[52:53], 0, s[50:51]
	s_waitcnt lgkmcnt(0)
	v_add_f32_e32 v50, v50, v51
	global_store_dword v[52:53], v50, off

.LBB0_410:
	v_mul_f32_e32 v47, v47, v47
	v_mul_f32_e32 v43, v43, v43
	v_mul_f32_e32 v39, v39, v39
	v_mul_f32_e32 v35, v35, v35
	v_fmac_f32_e32 v47, v46, v46
	v_mul_f32_e32 v46, v49, v49
	v_fmac_f32_e32 v43, v42, v42
	v_mul_f32_e32 v42, v45, v45
	v_fmac_f32_e32 v39, v38, v38
	v_mul_f32_e32 v38, v41, v41
	v_fmac_f32_e32 v35, v34, v34
	v_mul_f32_e32 v34, v37, v37
	v_fmac_f32_e32 v46, v48, v48
	v_fmac_f32_e32 v42, v44, v44
	v_fmac_f32_e32 v38, v40, v40
	v_fmac_f32_e32 v34, v36, v36
	v_add_f32_e32 v46, v47, v46
	v_add_f32_e32 v42, v43, v42
	v_add_f32_e32 v38, v39, v38
	v_add_f32_e32 v34, v35, v34
	v_add_f32_e32 v42, v46, v42
	v_add_f32_e32 v34, v38, v34
	v_add_f32_e32 v34, v42, v34
	v_mov_b32_e32 v35, v34
	s_nop 1
	v_permlane16_swap_b32 v34, v35
	s_nop 1
	v_add_f32_e32 v34, v34, v35
	v_mov_b32_e32 v35, v34
	s_nop 1
	v_permlane32_swap_b32 v34, v35
	s_nop 1
	s_and_saveexec_b64 s[56:57], s[36:37]
	s_cbranch_execz .LBB0_412
	v_lshlrev_b64 v[36:37], 6, v[102:103]
	v_lshl_add_u64 v[36:37], s[48:49], 0, v[36:37]
	v_lshl_add_u64 v[36:37], s[72:73], 2, v[36:37]
	s_lshl_b32 s50, s77, 2
	v_lshl_add_u64 v[36:37], v[36:37], 0, s[50:51]
	s_waitcnt lgkmcnt(0)
	v_add_f32_e32 v34, v34, v35
	global_store_dword v[36:37], v34, off

.LBB0_418:
	v_mul_f32_e32 v31, v31, v31
	v_mul_f32_e32 v27, v27, v27
	v_mul_f32_e32 v23, v23, v23
	v_mul_f32_e32 v19, v19, v19
	v_fmac_f32_e32 v31, v30, v30
	v_mul_f32_e32 v30, v33, v33
	v_fmac_f32_e32 v27, v26, v26
	v_mul_f32_e32 v26, v29, v29
	v_fmac_f32_e32 v23, v22, v22
	v_mul_f32_e32 v22, v25, v25
	v_fmac_f32_e32 v19, v18, v18
	v_mul_f32_e32 v18, v21, v21
	v_fmac_f32_e32 v30, v32, v32
	v_fmac_f32_e32 v26, v28, v28
	v_fmac_f32_e32 v22, v24, v24
	v_fmac_f32_e32 v18, v20, v20
	v_add_f32_e32 v30, v31, v30
	v_add_f32_e32 v26, v27, v26
	v_add_f32_e32 v22, v23, v22
	v_add_f32_e32 v18, v19, v18
	v_add_f32_e32 v26, v30, v26
	v_add_f32_e32 v18, v22, v18
	v_add_f32_e32 v18, v26, v18
	v_mov_b32_e32 v19, v18
	s_nop 1
	v_permlane16_swap_b32 v18, v19
	s_nop 1
	v_add_f32_e32 v18, v18, v19
	v_mov_b32_e32 v19, v18
	s_nop 1
	v_permlane32_swap_b32 v18, v19
	s_nop 1
	s_and_saveexec_b64 s[56:57], s[36:37]
	s_cbranch_execz .LBB0_420
	v_lshlrev_b64 v[20:21], 6, v[98:99]
	v_lshl_add_u64 v[20:21], s[48:49], 0, v[20:21]
	v_lshl_add_u64 v[20:21], s[72:73], 2, v[20:21]
	s_lshl_b32 s50, s77, 2
	v_lshl_add_u64 v[20:21], v[20:21], 0, s[50:51]
	s_waitcnt lgkmcnt(0)
	v_add_f32_e32 v18, v18, v19
	global_store_dword v[20:21], v18, off

.LBB0_426:
	v_mul_f32_e32 v15, v15, v15
	v_mul_f32_e32 v11, v11, v11
	v_mul_f32_e32 v7, v7, v7
	v_mul_f32_e32 v3, v3, v3
	v_fmac_f32_e32 v15, v14, v14
	v_mul_f32_e32 v14, v17, v17
	v_fmac_f32_e32 v11, v10, v10
	v_mul_f32_e32 v10, v13, v13
	v_fmac_f32_e32 v7, v6, v6
	v_mul_f32_e32 v6, v9, v9
	v_fmac_f32_e32 v3, v2, v2
	v_mul_f32_e32 v2, v5, v5
	v_fmac_f32_e32 v14, v16, v16
	v_fmac_f32_e32 v10, v12, v12
	v_fmac_f32_e32 v6, v8, v8
	v_fmac_f32_e32 v2, v4, v4
	v_add_f32_e32 v14, v15, v14
	v_add_f32_e32 v10, v11, v10
	v_add_f32_e32 v6, v7, v6
	v_add_f32_e32 v2, v3, v2
	v_add_f32_e32 v10, v14, v10
	v_add_f32_e32 v2, v6, v2
	v_add_f32_e32 v2, v10, v2
	v_mov_b32_e32 v3, v2
	s_nop 1
	v_permlane16_swap_b32 v2, v3
	s_nop 1
	v_add_f32_e32 v2, v2, v3
	v_mov_b32_e32 v3, v2
	s_nop 1
	v_permlane32_swap_b32 v2, v3
	s_nop 1
	s_and_saveexec_b64 s[40:41], s[36:37]
	s_cbranch_execz .LBB0_355
	v_lshlrev_b64 v[4:5], 6, v[94:95]
	v_lshl_add_u64 v[4:5], s[48:49], 0, v[4:5]
	v_lshl_add_u64 v[4:5], s[72:73], 2, v[4:5]
	s_lshl_b32 s50, s77, 2
	v_lshl_add_u64 v[4:5], v[4:5], 0, s[50:51]
	s_waitcnt lgkmcnt(0)
	v_add_f32_e32 v2, v2, v3
	global_store_dword v[4:5], v2, off
	s_branch .LBB0_355
